# adds hand-written scan phase: score tiles split between wave pairs via LDS exchange, Q/K/V staged through LDS, prefetch distance 2
# speedup vs baseline: 1.0045x; 1.0045x over previous
; #define LAS __attribute__((address_space(3)))
; __device__ void scan_phase(LAS unsigned char* lds, const Params& p) {
;     const int tid = threadIdx.x, w = __builtin_amdgcn_readfirstlane(tid >> 6), lane = tid & 63, ln = lane & 15, lq = lane >> 4;
;     constexpr int QST = 136, VST = 36;
;     constexpr int OFF_KS = 17408, OFF_V = 34816, BUFB = 39424;
;     LAS bf16_t* Sr = (LAS bf16_t*)(lds + 2 * BUFB);
;     LAS float* scs = (LAS float*)(lds + 2 * BUFB + 9216);
;     bf16_t* O = (bf16_t*)p.out;
;     bf16_t* Odummy = (bf16_t*)(p.ws + WS_A) + (size_t)blockIdx.x * 64 * 512;
;     const float* RT = (const float*)(p.ws + WS_RT);
;     const int eb = w & 1, tb = w >> 1;
;     if (w >= 4) __builtin_amdgcn_s_setprio(1);
;     for (int item = blockIdx.x; item < 256; item += gridDim.x) {
;         const int seq = (item & 7) + 8 * (item >> 5), es = (item >> 3) & 3;
;         const int dir = seq & 1, h = (seq >> 1) & 3, b = seq >> 3;
;         const char* Qx = (const char*)((const bf16_t*)(p.ws + (dir ? WS_QB : WS_QF)) + h * 128);
;         const char* Kx = (const char*)((const bf16_t*)(p.ws + (dir ? WS_KB : WS_KF)) + h * 128);
;         const char* Vx = (const char*)((const bf16_t*)(p.ws + WS_V) + h * 128 + es * 32);
;         const char* Rx = (const char*)(RT + (size_t)dir * NCHUNK * 512 + h * 128);
;         const char* Tx = (const char*)(RT + (size_t)(2 + dir) * NCHUNK * 512 + h * 128);
;         const unsigned qoff0 = (unsigned)((dir ? 63 - (tid >> 4) : (tid >> 4)) * 1024 + (tid & 15) * 16), qstep = dir ? (unsigned)-32768 : 32768u;
;         const unsigned voff = (unsigned)((dir ? 63 - (tid >> 3) : (tid >> 3)) * 1024 + (tid & 7) * 8), roff = (unsigned)(tid & 127) * 4u;
;         f32x4 S[2] = {(f32x4){0.f, 0.f, 0.f, 0.f}, (f32x4){0.f, 0.f, 0.f, 0.f}};
;         float tailp = 0.f;
;         u32x4 k4A[2], k4B[2], k4C[2], k4D[2]; u32x4 q4A[2], q4B[2], q4C[2], q4D[2]; u32x2 v4A, v4B, v4C, v4D; float rvA, tlA, rvB, tlB, rvC, tlC, rvD, tlD;
;     ...
;         SCAN_LOAD(0, k4A, q4A, v4A, rvA, tlA); SCAN_LOAD(1, k4B, q4B, v4B, rvB, tlB); SCAN_LOAD(2, k4C, q4C, v4C, rvC, tlC); SCAN_LOAD(3, k4D, q4D, v4D, rvD, tlD);
;         SCAN_STAGE(0, k4A, q4A, v4A, rvA, tlA); SCAN_LOAD(4, k4A, q4A, v4A, rvA, tlA);
.LBB0_256:
	s_cmp_lt_i32 s72, 4
	s_cselect_b64 s[8:9], -1, 0
	s_waitcnt lgkmcnt(0)
	s_and_b64 s[38:39], s[8:9], s[6:7]
	s_andn2_b64 vcc, exec, s[38:39]
	s_cbranch_vccnz .LBB0_308
	v_lshrrev_b32_e32 v1, 6, v0
	s_nop 0
	v_readfirstlane_b32 s6, v1
	s_lshr_b32 s7, s6, 1
	s_and_b32 s8, s6, 1
	s_mov_b32 s9, s2
	s_load_dword s35, s[0:1], 0x98
	s_cmp_ge_u32 s7, 2
	s_cselect_b32 s11, 1, 0
	s_cmp_lt_u32 s6, 2
	s_cselect_b32 s12, 1, 0
	s_cmp_le_u32 s8, s7
	s_cselect_b32 s13, 1, 0
	s_add_u32 s3, s8, 2
	s_cmp_le_u32 s3, s7
	s_cselect_b32 s14, 1, 0
	v_and_b32_e32 v88, 15, v0
	v_bfe_u32 v89, v0, 4, 2
	v_lshrrev_b32_e32 v144, 2, v88
	v_and_b32_e32 v145, 3, v0
	v_and_b32_e32 v146, 63, v0
	v_lshlrev_b32_e32 v147, 2, v89
	v_add_u32_e32 v1, 0, v147
	v_cmp_le_u32_e64 s[94:95], v1, v88
	v_add_u32_e32 v1, 1, v147
	v_cmp_le_u32_e64 s[96:97], v1, v88
	v_add_u32_e32 v1, 2, v147
	v_cmp_le_u32_e64 s[98:99], v1, v88
	v_add_u32_e32 v1, 3, v147
	v_cmp_le_u32_e64 vcc, v1, v88
	s_cmp_eq_u32 s8, s7
	s_cselect_b64 s[76:77], s[94:95], -1
	s_cselect_b64 s[78:79], s[96:97], -1
	s_cselect_b64 s[80:81], s[98:99], -1
	s_cselect_b64 s[82:83], vcc, -1
	s_add_u32 s3, s8, 2
	s_cmp_eq_u32 s3, s7
	s_cselect_b64 s[84:85], s[94:95], -1
	s_cselect_b64 s[88:89], s[96:97], -1
	s_cselect_b64 s[90:91], s[98:99], -1
	s_cselect_b64 s[92:93], vcc, -1
	v_lshrrev_b32_e32 v1, 4, v0
	v_mul_u32_u24_e32 v131, 272, v1
	v_lshl_add_u32 v131, v88, 4, v131
	v_lshrrev_b32_e32 v1, 3, v0
	v_mul_u32_u24_e32 v132, 72, v1
	v_and_b32_e32 v1, 7, v0
	v_lshl_add_u32 v132, v1, 3, v132
	v_and_b32_e32 v1, 0x7f, v0
	v_lshlrev_b32_e32 v129, 2, v1
	v_add_u32_e32 v133, 88064, v129
	s_lshl_b32 s3, s7, 7
	s_add_u32 s3, s3, 88064
	v_lshl_add_u32 v134, v88, 2, s3
	s_mul_i32 s3, s7, 2304
	s_lshl_b32 s4, s8, 5
	s_add_u32 s3, s3, s4
	s_add_u32 s3, s3, 78848
	v_mul_u32_u24_e32 v135, 72, v88
	v_lshl_add_u32 v135, v89, 3, v135
	v_add_u32_e32 v135, s3, v135
	s_mul_i32 s3, s8, 4352
	v_mul_u32_u24_e32 v136, 272, v88
	v_lshl_add_u32 v136, v89, 4, v136
	v_add_u32_e32 v136, s3, v136
	s_mul_i32 s3, s7, 4352
	v_mul_u32_u24_e32 v148, 272, v88
	v_lshl_add_u32 v148, v89, 4, v148
	v_add_u32_e32 v148, s3, v148
	s_lshl_b32 s3, s7, 11
	s_add_u32 s3, s3, 89088
	v_lshl_add_u32 v138, v146, 4, s3
	s_lshl_b32 s4, s8, 3
	v_add_u32_e32 v137, s4, v138
	v_lshl_add_u32 v1, v89, 3, v144
	v_mul_u32_u24_e32 v139, 72, v1
	v_lshl_add_u32 v139, v145, 3, v139
	s_lshl_b32 s4, s8, 5
	s_add_u32 s3, s4, 78848
	v_add_u32_e32 v139, s3, v139
	v_lshl_add_u32 v1, v89, 2, v144
	v_mul_u32_u24_e32 v140, 72, v1
	v_lshl_add_u32 v140, v145, 3, v140
	v_add_u32_e32 v140, s4, v140
	v_mul_u32_u24_e32 v141, 272, v1
	v_lshl_add_u32 v141, v145, 3, v141
	s_lshl_b32 s3, s7, 6
	v_add_u32_e32 v141, s3, v141
	v_add_u32_e32 v82, 39424, v131
	v_add_u32_e32 v83, 39424, v132
	v_add_u32_e32 v84, 39424, v148
	v_add_u32_e32 v85, 39424, v136
	v_add_u32_e32 v86, 39424, v140
	v_add_u32_e32 v87, 39424, v141
	s_waitcnt lgkmcnt(0)
	s_cmp_gt_u32 s9, 0xff
	s_cbranch_scc1 .Lscan_done
.Lscan_item:
	s_and_b32 s10, s9, 1
	s_lshr_b32 s3, s9, 1
	s_and_b32 s3, s3, 3
	s_lshr_b32 s4, s9, 5
	s_lshr_b32 s5, s9, 3
	s_and_b32 s5, s5, 3
	s_cmp_eq_u32 s10, 0
	s_cselect_b32 s15, 1, -1
	s_cselect_b32 s64, 0, 3
	s_cselect_b32 s65, -4, 0x43
	s_lshl_b32 s16, s4, 2
	s_add_u32 s16, s16, 0x200
	s_lshl_b32 s17, s4, 6
	s_add_u32 s16, s16, s64
	s_add_i32 s17, s17, s65
	s_lshl_b32 s3, s3, 8
	s_lshl_b32 s5, s5, 6
	s_cmp_eq_u32 s10, 0
	s_mov_b32 s65, 0x5100000
	s_cselect_b32 s64, s65, 0x7300000
	s_add_u32 s64, s64, s3
	s_add_u32 s18, s70, s64
	s_addc_u32 s19, s71, 0
	s_cmp_eq_u32 s10, 0
	s_mov_b32 s65, 0x9500000
	s_cselect_b32 s64, s65, 0xb700000
	s_add_u32 s64, s64, s3
	s_add_u32 s20, s70, s64
	s_addc_u32 s21, s71, 0
	s_add_u32 s64, s3, s5
	s_add_u32 s65, s64, 0xd900000
	s_add_u32 s22, s70, s65
	s_addc_u32 s23, s71, 0
	s_lshl_b32 s65, s10, 25
	s_add_u32 s64, s64, s65
	s_add_u32 s28, s68, s64
	s_addc_u32 s29, s69, 0
	s_mul_i32 s64, s10, 0x110000
	s_lshl_b32 s65, s3, 1
	s_add_u32 s64, s64, s65
	s_add_u32 s64, s64, 0x15b00000
	s_add_u32 s24, s70, s64
	s_addc_u32 s25, s71, 0
	s_add_u32 s26, s24, 0x220000
	s_addc_u32 s27, s25, 0
	s_lshl_b32 s64, s9, 16
	s_add_u32 s64, s64, 0xd00000
	s_add_u32 s30, s70, s64
	s_addc_u32 s31, s71, 0
	s_mul_i32 s5, s10, 63
	s_lshl_b32 s3, s7, 4
	v_add_u32_e32 v1, s3, v88
	v_xor_b32_e32 v1, s5, v1
	v_lshlrev_b32_e32 v1, 10, v1
	v_lshl_add_u32 v125, v89, 4, v1
	s_lshl_b32 s3, s8, 5
	v_lshl_add_u32 v130, v89, 3, v1
	v_add_u32_e32 v130, s3, v130
	v_lshrrev_b32_e32 v1, 4, v0
	v_xor_b32_e32 v147, s5, v1
	v_lshlrev_b32_e32 v147, 10, v147
	v_lshl_add_u32 v126, v88, 4, v147
	v_add_u32_e32 v1, 32, v1
	v_xor_b32_e32 v147, s5, v1
	v_lshlrev_b32_e32 v147, 10, v147
	v_lshl_add_u32 v127, v88, 4, v147
	v_lshrrev_b32_e32 v1, 3, v0
	v_xor_b32_e32 v1, s5, v1
	v_lshlrev_b32_e32 v1, 10, v1
	v_and_b32_e32 v147, 7, v0
	v_lshl_add_u32 v128, v147, 3, v1
	v_mov_b32_e32 v114, 0
	v_mov_b32_e32 v115, 0
	v_mov_b32_e32 v116, 0
	v_mov_b32_e32 v117, 0
	v_mov_b32_e32 v118, 0
	v_mov_b32_e32 v119, 0
	v_mov_b32_e32 v120, 0
	v_mov_b32_e32 v121, 0
	v_mov_b32_e32 v124, 0
	v_mov_b32_e32 v190, 0
	v_mov_b32_e32 v191, 0
	v_mov_b32_e32 v192, 0
	v_mov_b32_e32 v193, 0
	v_mov_b32_e32 v206, 0
	v_mov_b32_e32 v207, 0
	s_mov_b32 s3, 0
	s_cmp_lt_u32 s3, 4
	s_cselect_b32 s4, s16, s17
	s_mul_i32 s5, s3, s15
	s_add_i32 s4, s4, s5
	s_lshl_b32 s5, s4, 16
	s_lshl_b32 s4, s4, 11
	s_add_u32 s40, s18, s5
	s_addc_u32 s41, s19, 0
	s_add_u32 s42, s20, s5
	s_addc_u32 s43, s21, 0
	s_add_u32 s44, s22, s5
	s_addc_u32 s45, s23, 0
	s_add_u32 s46, s24, s4
	s_addc_u32 s47, s25, 0
	s_add_u32 s50, s26, s4
	s_addc_u32 s51, s27, 0
	global_load_dwordx4 v[2:5], v126, s[40:41]
	global_load_dwordx4 v[6:9], v127, s[40:41]
	global_load_dwordx4 v[10:13], v126, s[42:43]
	global_load_dwordx4 v[14:17], v127, s[42:43]
	global_load_dwordx2 v[18:19], v128, s[44:45]
	global_load_dword v20, v129, s[46:47]
	global_load_dword v21, v129, s[50:51]
	global_store_dwordx2 v130, v[206:207], s[30:31]
	s_mov_b32 s3, 1
	s_cmp_lt_u32 s3, 4
	s_cselect_b32 s4, s16, s17
	s_mul_i32 s5, s3, s15
	s_add_i32 s4, s4, s5
	s_lshl_b32 s5, s4, 16
	s_lshl_b32 s4, s4, 11
	s_add_u32 s40, s18, s5
	s_addc_u32 s41, s19, 0
	s_add_u32 s42, s20, s5
	s_addc_u32 s43, s21, 0
	s_add_u32 s44, s22, s5
	s_addc_u32 s45, s23, 0
	s_add_u32 s46, s24, s4
	s_addc_u32 s47, s25, 0
	s_add_u32 s50, s26, s4
	s_addc_u32 s51, s27, 0
	global_load_dwordx4 v[22:25], v126, s[40:41]
	global_load_dwordx4 v[26:29], v127, s[40:41]
	global_load_dwordx4 v[30:33], v126, s[42:43]
	global_load_dwordx4 v[34:37], v127, s[42:43]
	global_load_dwordx2 v[38:39], v128, s[44:45]
	global_load_dword v40, v129, s[46:47]
	global_load_dword v41, v129, s[50:51]
	global_store_dwordx2 v130, v[206:207], s[30:31]
	s_waitcnt vmcnt(9)
	ds_write_b128 v131, v[2:5] offset:0
	ds_write_b128 v131, v[6:9] offset:8704
	ds_write_b128 v131, v[10:13] offset:17408
	ds_write_b128 v131, v[14:17] offset:26112
	ds_write_b64 v132, v[18:19] offset:34816
	s_cmp_eq_u32 s12, 0
	s_cbranch_scc1 .Lscan_nosc_pro
; #define SCAN_BAR() asm volatile("s_waitcnt lgkmcnt(0)\n\ts_barrier" ::: "memory")
; __device__ void scan_phase(LAS unsigned char* lds, const Params& p) {
;     ...
;         for (int n0 = 0; n0 < 68; n0 += 4) {
;             SCAN_STAGE(1, k4B, q4B, v4B, rvB, tlB); SCAN_LOAD(min(n0 + 5, 67), k4B, q4B, v4B, rvB, tlB); SCAN_MAT(0, n0); SCAN_BAR();
	v_add_f32_e32 v142, v20, v124
	v_mul_f32_e32 v142, 0x3fb8aa3b, v142
	v_exp_f32_e32 v142, v142
	v_mov_b32_e32 v124, v21
	ds_write_b32 v133, v142 offset:0
.Lscan_nosc_pro:
	s_waitcnt lgkmcnt(0)
	s_barrier
	s_mov_b32 s34, 0
.Lscan_loop:
	ds_read_b32 v122, v134 offset:0
	ds_read_b32 v123, v134 offset:64
	ds_read_b128 v[208:211], v148 offset:0
	ds_read_b128 v[212:215], v148 offset:64
	ds_read_b128 v[216:219], v148 offset:128
	ds_read_b128 v[220:223], v148 offset:192
	s_cmp_eq_u32 s13, 0
	s_cbranch_scc1 .Lscan_nox_0
	ds_read_b128 v[150:153], v136 offset:17408
	ds_read_b128 v[154:157], v136 offset:17472
	ds_read_b128 v[158:161], v136 offset:17536
	ds_read_b128 v[162:165], v136 offset:17600
.Lscan_nox_0:
	s_cmp_eq_u32 s14, 0
	s_cbranch_scc1 .Lscan_noy_0
	ds_read_b128 v[166:169], v136 offset:26112
	ds_read_b128 v[170:173], v136 offset:26176
	ds_read_b128 v[174:177], v136 offset:26240
	ds_read_b128 v[178:181], v136 offset:26304
.Lscan_noy_0:
	s_add_u32 s3, s34, 2
	s_min_u32 s3, s3, 0x43
	s_cmp_lt_u32 s3, 4
	s_cselect_b32 s4, s16, s17
	s_mul_i32 s5, s3, s15
	s_add_i32 s4, s4, s5
	s_lshl_b32 s5, s4, 16
	s_lshl_b32 s4, s4, 11
	s_add_u32 s40, s18, s5
	s_addc_u32 s41, s19, 0
	s_add_u32 s42, s20, s5
	s_addc_u32 s43, s21, 0
	s_add_u32 s44, s22, s5
	s_addc_u32 s45, s23, 0
	s_add_u32 s46, s24, s4
	s_addc_u32 s47, s25, 0
	s_add_u32 s50, s26, s4
	s_addc_u32 s51, s27, 0
	global_load_dwordx4 v[42:45], v126, s[40:41]
	global_load_dwordx4 v[46:49], v127, s[40:41]
	global_load_dwordx4 v[50:53], v126, s[42:43]
	global_load_dwordx4 v[54:57], v127, s[42:43]
	global_load_dwordx2 v[58:59], v128, s[44:45]
	global_load_dword v60, v129, s[46:47]
	global_load_dword v61, v129, s[50:51]
	s_waitcnt lgkmcnt(0)
	s_cmp_eq_u32 s13, 0
	s_cbranch_scc1 .Lscan_nox2_0
	v_mfma_f32_16x16x32_bf16 v[182:185], v[150:153], v[208:211], 0
	v_mfma_f32_16x16x32_bf16 v[182:185], v[154:157], v[212:215], v[182:185]
	v_mfma_f32_16x16x32_bf16 v[182:185], v[158:161], v[216:219], v[182:185]
	v_mfma_f32_16x16x32_bf16 v[182:185], v[162:165], v[220:223], v[182:185]
.Lscan_nox2_0:
	s_cmp_eq_u32 s14, 0
	s_cbranch_scc1 .Lscan_noy2_0
	v_mfma_f32_16x16x32_bf16 v[186:189], v[166:169], v[208:211], 0
	v_mfma_f32_16x16x32_bf16 v[186:189], v[170:173], v[212:215], v[186:189]
	v_mfma_f32_16x16x32_bf16 v[186:189], v[174:177], v[216:219], v[186:189]
	v_mfma_f32_16x16x32_bf16 v[186:189], v[178:181], v[220:223], v[186:189]
.Lscan_noy2_0:
	v_mul_f32_e32 v114, v114, v122
	v_mul_f32_e32 v115, v115, v122
	v_mul_f32_e32 v116, v116, v122
	v_mul_f32_e32 v117, v117, v122
	v_mul_f32_e32 v118, v118, v123
	v_mul_f32_e32 v119, v119, v123
	v_mul_f32_e32 v120, v120, v123
	v_mul_f32_e32 v121, v121, v123
	v_cvt_pk_bf16_f32 v142, v114, v115
	v_cvt_pk_bf16_f32 v143, v116, v117
	v_cvt_pk_bf16_f32 v144, v118, v119
	v_cvt_pk_bf16_f32 v145, v120, v121
	ds_write_b64 v135, v[142:143]
	ds_write_b64 v135, v[144:145] offset:1152
	s_cmp_eq_u32 s13, 0
	s_cbranch_scc1 .Lscan_nox3_0
	v_cndmask_b32_e64 v182, 0, v182, s[76:77]
	v_cndmask_b32_e64 v183, 0, v183, s[78:79]
	v_cndmask_b32_e64 v184, 0, v184, s[80:81]
	v_cndmask_b32_e64 v185, 0, v185, s[82:83]
	v_cvt_pk_bf16_f32 v190, v182, v183
	v_cvt_pk_bf16_f32 v191, v184, v185
.Lscan_nox3_0:
	s_cmp_eq_u32 s14, 0
	s_cbranch_scc1 .Lscan_noy3_0
	v_cndmask_b32_e64 v186, 0, v186, s[84:85]
	v_cndmask_b32_e64 v187, 0, v187, s[88:89]
	v_cndmask_b32_e64 v188, 0, v188, s[90:91]
	v_cndmask_b32_e64 v189, 0, v189, s[92:93]
	v_cvt_pk_bf16_f32 v192, v186, v187
	v_cvt_pk_bf16_f32 v193, v188, v189
.Lscan_noy3_0:
	ds_write_b64 v137, v[190:191]
	ds_write_b64 v137, v[192:193] offset:1024
	s_waitcnt lgkmcnt(0)
	s_barrier
	ds_read_b64_tr_b16 v[150:151], v139 offset:0
	ds_read_b64_tr_b16 v[152:153], v139 offset:288
	ds_read_b64_tr_b16 v[154:155], v139 offset:2304
	ds_read_b64_tr_b16 v[156:157], v139 offset:2592
	ds_read_b64_tr_b16 v[158:159], v139 offset:4608
	ds_read_b64_tr_b16 v[160:161], v139 offset:4896
	ds_read_b64_tr_b16 v[162:163], v139 offset:6912
	ds_read_b64_tr_b16 v[164:165], v139 offset:7200
	ds_read_b64_tr_b16 v[166:167], v140 offset:34816
	ds_read_b64_tr_b16 v[168:169], v140 offset:35968
	ds_read_b64_tr_b16 v[170:171], v140 offset:37120
	ds_read_b64_tr_b16 v[172:173], v140 offset:38272
	ds_read_b128 v[194:197], v138
	ds_read_b128 v[198:201], v138 offset:1024
	s_waitcnt lgkmcnt(12)
	v_mfma_f32_16x16x32_bf16 v[202:205], v[150:153], v[208:211], 0
	ds_read_b64_tr_b16 v[174:175], v141 offset:17408
	ds_read_b64_tr_b16 v[176:177], v141 offset:21760
	s_waitcnt lgkmcnt(12)
	v_mfma_f32_16x16x32_bf16 v[202:205], v[154:157], v[212:215], v[202:205]
	ds_read_b64_tr_b16 v[178:179], v141 offset:17440
	ds_read_b64_tr_b16 v[180:181], v141 offset:21792
	s_waitcnt lgkmcnt(12)
	v_mfma_f32_16x16x32_bf16 v[202:205], v[158:161], v[216:219], v[202:205]
	ds_read_b64_tr_b16 v[182:183], v141 offset:26112
	ds_read_b64_tr_b16 v[184:185], v141 offset:30464
	s_waitcnt lgkmcnt(12)
	v_mfma_f32_16x16x32_bf16 v[202:205], v[162:165], v[220:223], v[202:205]
	ds_read_b64_tr_b16 v[186:187], v141 offset:26144
	ds_read_b64_tr_b16 v[188:189], v141 offset:30496
	s_waitcnt lgkmcnt(9)
	v_mfma_f32_16x16x32_bf16 v[202:205], v[166:169], v[194:197], v[202:205]
	s_waitcnt lgkmcnt(8)
	s_cmp_eq_u32 s11, 0
	s_cbranch_scc1 .Lscan_nopv1_0
	v_mfma_f32_16x16x32_bf16 v[202:205], v[170:173], v[198:201], v[202:205]
.Lscan_nopv1_0:
	s_waitcnt lgkmcnt(6)
	v_mfma_f32_16x16x32_bf16 v[114:117], v[166:169], v[174:177], v[114:117]
	s_waitcnt lgkmcnt(4)
	v_mfma_f32_16x16x32_bf16 v[118:121], v[166:169], v[178:181], v[118:121]
	s_waitcnt lgkmcnt(2)
	v_mfma_f32_16x16x32_bf16 v[114:117], v[170:173], v[182:185], v[114:117]
	s_waitcnt lgkmcnt(0)
	v_mfma_f32_16x16x32_bf16 v[118:121], v[170:173], v[186:189], v[118:121]
	s_waitcnt vmcnt(8)
	ds_write_b128 v82, v[22:25] offset:0
	ds_write_b128 v82, v[26:29] offset:8704
	ds_write_b128 v82, v[30:33] offset:17408
	ds_write_b128 v82, v[34:37] offset:26112
	ds_write_b64 v83, v[38:39] offset:34816
	s_cmp_eq_u32 s12, 0
	s_cbranch_scc1 .Lscan_nosc_0
	v_add_f32_e32 v142, v40, v124
	v_mul_f32_e32 v142, 0x3fb8aa3b, v142
	v_exp_f32_e32 v142, v142
	v_mov_b32_e32 v124, v41
	ds_write_b32 v133, v142 offset:512
.Lscan_nosc_0:
	s_add_u32 s3, s34, 0
	s_cmp_lt_u32 s3, 4
	s_cselect_b32 s4, s16, s17
	s_mul_i32 s5, s3, s15
	s_add_i32 s4, s4, s5
	s_lshl_b32 s4, s4, 16
	s_add_u32 s64, s28, s4
	s_addc_u32 s65, s29, 0
	s_cmp_eq_u32 s34, 0
	s_cselect_b32 s64, s30, s64
	s_cselect_b32 s65, s31, s65
	v_cvt_pk_bf16_f32 v206, v202, v203
	v_cvt_pk_bf16_f32 v207, v204, v205
	global_store_dwordx2 v130, v[206:207], s[64:65]
	s_waitcnt lgkmcnt(0)
	s_barrier
	ds_read_b32 v122, v134 offset:512
	ds_read_b32 v123, v134 offset:576
	ds_read_b128 v[208:211], v84 offset:0
	ds_read_b128 v[212:215], v84 offset:64
	ds_read_b128 v[216:219], v84 offset:128
	ds_read_b128 v[220:223], v84 offset:192
	s_cmp_eq_u32 s13, 0
	s_cbranch_scc1 .Lscan_nox_1
	ds_read_b128 v[150:153], v85 offset:17408
	ds_read_b128 v[154:157], v85 offset:17472
	ds_read_b128 v[158:161], v85 offset:17536
	ds_read_b128 v[162:165], v85 offset:17600
.Lscan_nox_1:
	s_cmp_eq_u32 s14, 0
	s_cbranch_scc1 .Lscan_noy_1
	ds_read_b128 v[166:169], v85 offset:26112
	ds_read_b128 v[170:173], v85 offset:26176
	ds_read_b128 v[174:177], v85 offset:26240
	ds_read_b128 v[178:181], v85 offset:26304
.Lscan_noy_1:
	s_add_u32 s3, s34, 3
	s_min_u32 s3, s3, 0x43
	s_cmp_lt_u32 s3, 4
	s_cselect_b32 s4, s16, s17
	s_mul_i32 s5, s3, s15
	s_add_i32 s4, s4, s5
	s_lshl_b32 s5, s4, 16
	s_lshl_b32 s4, s4, 11
	s_add_u32 s40, s18, s5
	s_addc_u32 s41, s19, 0
	s_add_u32 s42, s20, s5
	s_addc_u32 s43, s21, 0
	s_add_u32 s44, s22, s5
	s_addc_u32 s45, s23, 0
	s_add_u32 s46, s24, s4
	s_addc_u32 s47, s25, 0
	s_add_u32 s50, s26, s4
	s_addc_u32 s51, s27, 0
	global_load_dwordx4 v[62:65], v126, s[40:41]
	global_load_dwordx4 v[66:69], v127, s[40:41]
	global_load_dwordx4 v[70:73], v126, s[42:43]
	global_load_dwordx4 v[74:77], v127, s[42:43]
	global_load_dwordx2 v[78:79], v128, s[44:45]
	global_load_dword v80, v129, s[46:47]
	global_load_dword v81, v129, s[50:51]
	s_waitcnt lgkmcnt(0)
	s_cmp_eq_u32 s13, 0
	s_cbranch_scc1 .Lscan_nox2_1
	v_mfma_f32_16x16x32_bf16 v[182:185], v[150:153], v[208:211], 0
	v_mfma_f32_16x16x32_bf16 v[182:185], v[154:157], v[212:215], v[182:185]
	v_mfma_f32_16x16x32_bf16 v[182:185], v[158:161], v[216:219], v[182:185]
	v_mfma_f32_16x16x32_bf16 v[182:185], v[162:165], v[220:223], v[182:185]

.Lscan_noy3_1:
	ds_write_b64 v137, v[190:191]
	ds_write_b64 v137, v[192:193] offset:1024
	s_waitcnt lgkmcnt(0)
	s_barrier
	ds_read_b64_tr_b16 v[150:151], v139 offset:0
	ds_read_b64_tr_b16 v[152:153], v139 offset:288
	ds_read_b64_tr_b16 v[154:155], v139 offset:2304
	ds_read_b64_tr_b16 v[156:157], v139 offset:2592
	ds_read_b64_tr_b16 v[158:159], v139 offset:4608
	ds_read_b64_tr_b16 v[160:161], v139 offset:4896
	ds_read_b64_tr_b16 v[162:163], v139 offset:6912
	ds_read_b64_tr_b16 v[164:165], v139 offset:7200
	ds_read_b64_tr_b16 v[166:167], v86 offset:34816
	ds_read_b64_tr_b16 v[168:169], v86 offset:35968
	ds_read_b64_tr_b16 v[170:171], v86 offset:37120
	ds_read_b64_tr_b16 v[172:173], v86 offset:38272
	ds_read_b128 v[194:197], v138
	ds_read_b128 v[198:201], v138 offset:1024
	s_waitcnt lgkmcnt(12)
	v_mfma_f32_16x16x32_bf16 v[202:205], v[150:153], v[208:211], 0
	ds_read_b64_tr_b16 v[174:175], v87 offset:17408
	ds_read_b64_tr_b16 v[176:177], v87 offset:21760
	s_waitcnt lgkmcnt(12)
	v_mfma_f32_16x16x32_bf16 v[202:205], v[154:157], v[212:215], v[202:205]
	ds_read_b64_tr_b16 v[178:179], v87 offset:17440
	ds_read_b64_tr_b16 v[180:181], v87 offset:21792
	s_waitcnt lgkmcnt(12)
	v_mfma_f32_16x16x32_bf16 v[202:205], v[158:161], v[216:219], v[202:205]
	ds_read_b64_tr_b16 v[182:183], v87 offset:26112
	ds_read_b64_tr_b16 v[184:185], v87 offset:30464
	s_waitcnt lgkmcnt(12)
	v_mfma_f32_16x16x32_bf16 v[202:205], v[162:165], v[220:223], v[202:205]
	ds_read_b64_tr_b16 v[186:187], v87 offset:26144
	ds_read_b64_tr_b16 v[188:189], v87 offset:30496
	s_waitcnt lgkmcnt(9)
	v_mfma_f32_16x16x32_bf16 v[202:205], v[166:169], v[194:197], v[202:205]
	s_waitcnt lgkmcnt(8)
	s_cmp_eq_u32 s11, 0
	s_cbranch_scc1 .Lscan_nopv1_1
	v_mfma_f32_16x16x32_bf16 v[202:205], v[170:173], v[198:201], v[202:205]
.Lscan_nopv1_1:
	s_waitcnt lgkmcnt(6)
	v_mfma_f32_16x16x32_bf16 v[114:117], v[166:169], v[174:177], v[114:117]
	s_waitcnt lgkmcnt(4)
	v_mfma_f32_16x16x32_bf16 v[118:121], v[166:169], v[178:181], v[118:121]
	s_waitcnt lgkmcnt(2)
	v_mfma_f32_16x16x32_bf16 v[114:117], v[170:173], v[182:185], v[114:117]
	s_waitcnt lgkmcnt(0)
	v_mfma_f32_16x16x32_bf16 v[118:121], v[170:173], v[186:189], v[118:121]
	s_waitcnt vmcnt(8)
	ds_write_b128 v131, v[42:45] offset:0
	ds_write_b128 v131, v[46:49] offset:8704
	ds_write_b128 v131, v[50:53] offset:17408
	ds_write_b128 v131, v[54:57] offset:26112
	ds_write_b64 v132, v[58:59] offset:34816
	s_cmp_eq_u32 s12, 0
	s_cbranch_scc1 .Lscan_nosc_1
	v_add_f32_e32 v142, v60, v124
	v_mul_f32_e32 v142, 0x3fb8aa3b, v142
	v_exp_f32_e32 v142, v142
	v_mov_b32_e32 v124, v61
	ds_write_b32 v133, v142 offset:0
.Lscan_nosc_1:
	s_add_u32 s3, s34, 1
	s_cmp_lt_u32 s3, 4
	s_cselect_b32 s4, s16, s17
	s_mul_i32 s5, s3, s15
	s_add_i32 s4, s4, s5
	s_lshl_b32 s4, s4, 16
	s_add_u32 s64, s28, s4
	s_addc_u32 s65, s29, 0
	s_cmp_eq_u32 s34, 0
	s_cselect_b32 s64, s30, s64
	s_cselect_b32 s65, s31, s65
	v_cvt_pk_bf16_f32 v206, v202, v203
	v_cvt_pk_bf16_f32 v207, v204, v205
	global_store_dwordx2 v130, v[206:207], s[64:65]
	s_waitcnt lgkmcnt(0)
	s_barrier
	ds_read_b32 v122, v134 offset:0
	ds_read_b32 v123, v134 offset:64
	ds_read_b128 v[208:211], v148 offset:0
	ds_read_b128 v[212:215], v148 offset:64
	ds_read_b128 v[216:219], v148 offset:128
	ds_read_b128 v[220:223], v148 offset:192
	s_cmp_eq_u32 s13, 0
	s_cbranch_scc1 .Lscan_nox_2
	ds_read_b128 v[150:153], v136 offset:17408
	ds_read_b128 v[154:157], v136 offset:17472
	ds_read_b128 v[158:161], v136 offset:17536
	ds_read_b128 v[162:165], v136 offset:17600

.Lscan_noy_2:
	s_add_u32 s3, s34, 4
	s_min_u32 s3, s3, 0x43
	s_cmp_lt_u32 s3, 4
	s_cselect_b32 s4, s16, s17
	s_mul_i32 s5, s3, s15
	s_add_i32 s4, s4, s5
	s_lshl_b32 s5, s4, 16
	s_lshl_b32 s4, s4, 11
	s_add_u32 s40, s18, s5
	s_addc_u32 s41, s19, 0
	s_add_u32 s42, s20, s5
	s_addc_u32 s43, s21, 0
	s_add_u32 s44, s22, s5
	s_addc_u32 s45, s23, 0
	s_add_u32 s46, s24, s4
	s_addc_u32 s47, s25, 0
	s_add_u32 s50, s26, s4
	s_addc_u32 s51, s27, 0
	global_load_dwordx4 v[2:5], v126, s[40:41]
	global_load_dwordx4 v[6:9], v127, s[40:41]
	global_load_dwordx4 v[10:13], v126, s[42:43]
	global_load_dwordx4 v[14:17], v127, s[42:43]
	global_load_dwordx2 v[18:19], v128, s[44:45]
	global_load_dword v20, v129, s[46:47]
	global_load_dword v21, v129, s[50:51]
	s_waitcnt lgkmcnt(0)
	s_cmp_eq_u32 s13, 0
	s_cbranch_scc1 .Lscan_nox2_2
	v_mfma_f32_16x16x32_bf16 v[182:185], v[150:153], v[208:211], 0
	v_mfma_f32_16x16x32_bf16 v[182:185], v[154:157], v[212:215], v[182:185]
	v_mfma_f32_16x16x32_bf16 v[182:185], v[158:161], v[216:219], v[182:185]
	v_mfma_f32_16x16x32_bf16 v[182:185], v[162:165], v[220:223], v[182:185]

.Lscan_nopv1_2:
	s_waitcnt lgkmcnt(6)
	v_mfma_f32_16x16x32_bf16 v[114:117], v[166:169], v[174:177], v[114:117]
	s_waitcnt lgkmcnt(4)
	v_mfma_f32_16x16x32_bf16 v[118:121], v[166:169], v[178:181], v[118:121]
	s_waitcnt lgkmcnt(2)
	v_mfma_f32_16x16x32_bf16 v[114:117], v[170:173], v[182:185], v[114:117]
	s_waitcnt lgkmcnt(0)
	v_mfma_f32_16x16x32_bf16 v[118:121], v[170:173], v[186:189], v[118:121]
	s_waitcnt vmcnt(8)
	ds_write_b128 v82, v[62:65] offset:0
	ds_write_b128 v82, v[66:69] offset:8704
	ds_write_b128 v82, v[70:73] offset:17408
	ds_write_b128 v82, v[74:77] offset:26112
	ds_write_b64 v83, v[78:79] offset:34816
	s_cmp_eq_u32 s12, 0
	s_cbranch_scc1 .Lscan_nosc_2
	v_add_f32_e32 v142, v80, v124
	v_mul_f32_e32 v142, 0x3fb8aa3b, v142
	v_exp_f32_e32 v142, v142
	v_mov_b32_e32 v124, v81
	ds_write_b32 v133, v142 offset:512
.Lscan_nosc_2:
	s_add_u32 s3, s34, 2
	s_cmp_lt_u32 s3, 4
	s_cselect_b32 s4, s16, s17
	s_mul_i32 s5, s3, s15
	s_add_i32 s4, s4, s5
	s_lshl_b32 s4, s4, 16
	s_add_u32 s64, s28, s4
	s_addc_u32 s65, s29, 0
	s_cmp_eq_u32 s34, 0
	s_cselect_b32 s64, s30, s64
	s_cselect_b32 s65, s31, s65
	v_cvt_pk_bf16_f32 v206, v202, v203
	v_cvt_pk_bf16_f32 v207, v204, v205
	global_store_dwordx2 v130, v[206:207], s[64:65]
	s_waitcnt lgkmcnt(0)
	s_barrier
	ds_read_b32 v122, v134 offset:512
	ds_read_b32 v123, v134 offset:576
	ds_read_b128 v[208:211], v84 offset:0
	ds_read_b128 v[212:215], v84 offset:64
	ds_read_b128 v[216:219], v84 offset:128
	ds_read_b128 v[220:223], v84 offset:192
	s_cmp_eq_u32 s13, 0
	s_cbranch_scc1 .Lscan_nox_3
	ds_read_b128 v[150:153], v85 offset:17408
	ds_read_b128 v[154:157], v85 offset:17472
	ds_read_b128 v[158:161], v85 offset:17536
	ds_read_b128 v[162:165], v85 offset:17600

.Lscan_noy_3:
	s_add_u32 s3, s34, 5
	s_min_u32 s3, s3, 0x43
	s_cmp_lt_u32 s3, 4
	s_cselect_b32 s4, s16, s17
	s_mul_i32 s5, s3, s15
	s_add_i32 s4, s4, s5
	s_lshl_b32 s5, s4, 16
	s_lshl_b32 s4, s4, 11
	s_add_u32 s40, s18, s5
	s_addc_u32 s41, s19, 0
	s_add_u32 s42, s20, s5
	s_addc_u32 s43, s21, 0
	s_add_u32 s44, s22, s5
	s_addc_u32 s45, s23, 0
	s_add_u32 s46, s24, s4
	s_addc_u32 s47, s25, 0
	s_add_u32 s50, s26, s4
	s_addc_u32 s51, s27, 0
	global_load_dwordx4 v[22:25], v126, s[40:41]
	global_load_dwordx4 v[26:29], v127, s[40:41]
	global_load_dwordx4 v[30:33], v126, s[42:43]
	global_load_dwordx4 v[34:37], v127, s[42:43]
	global_load_dwordx2 v[38:39], v128, s[44:45]
	global_load_dword v40, v129, s[46:47]
	global_load_dword v41, v129, s[50:51]
	s_waitcnt lgkmcnt(0)
	s_cmp_eq_u32 s13, 0
	s_cbranch_scc1 .Lscan_nox2_3
	v_mfma_f32_16x16x32_bf16 v[182:185], v[150:153], v[208:211], 0
	v_mfma_f32_16x16x32_bf16 v[182:185], v[154:157], v[212:215], v[182:185]
	v_mfma_f32_16x16x32_bf16 v[182:185], v[158:161], v[216:219], v[182:185]
	v_mfma_f32_16x16x32_bf16 v[182:185], v[162:165], v[220:223], v[182:185]

; #define SCAN_BAR() asm volatile("s_waitcnt lgkmcnt(0)\n\ts_barrier" ::: "memory")
; __device__ void scan_phase(LAS unsigned char* lds, const Params& p) {
;     ...
;         SCAN_LOAD(0, k4A, q4A, v4A, rvA, tlA); SCAN_LOAD(1, k4B, q4B, v4B, rvB, tlB); SCAN_LOAD(2, k4C, q4C, v4C, rvC, tlC); SCAN_LOAD(3, k4D, q4D, v4D, rvD, tlD);
;         SCAN_STAGE(0, k4A, q4A, v4A, rvA, tlA); SCAN_LOAD(4, k4A, q4A, v4A, rvA, tlA);
;         SCAN_BAR();
; #pragma unroll 1
;         for (int n0 = 0; n0 < 68; n0 += 4) {
;             SCAN_STAGE(1, k4B, q4B, v4B, rvB, tlB); SCAN_LOAD(min(n0 + 5, 67), k4B, q4B, v4B, rvB, tlB); SCAN_MAT(0, n0); SCAN_BAR();
;             SCAN_STAGE(0, k4C, q4C, v4C, rvC, tlC); SCAN_LOAD(min(n0 + 6, 67), k4C, q4C, v4C, rvC, tlC); SCAN_MAT(1, n0 + 1); SCAN_BAR();
;             SCAN_STAGE(1, k4D, q4D, v4D, rvD, tlD); SCAN_LOAD(min(n0 + 7, 67), k4D, q4D, v4D, rvD, tlD); SCAN_MAT(0, n0 + 2); SCAN_BAR();
;             SCAN_STAGE(0, k4A, q4A, v4A, rvA, tlA); SCAN_LOAD(min(n0 + 8, 67), k4A, q4A, v4A, rvA, tlA); SCAN_MAT(1, n0 + 3); SCAN_BAR();
;         }
.Lscan_nopv1_3:
	s_waitcnt lgkmcnt(6)
	v_mfma_f32_16x16x32_bf16 v[114:117], v[166:169], v[174:177], v[114:117]
	s_waitcnt lgkmcnt(4)
	v_mfma_f32_16x16x32_bf16 v[118:121], v[166:169], v[178:181], v[118:121]
	s_waitcnt lgkmcnt(2)
	v_mfma_f32_16x16x32_bf16 v[114:117], v[170:173], v[182:185], v[114:117]
	s_waitcnt lgkmcnt(0)
	v_mfma_f32_16x16x32_bf16 v[118:121], v[170:173], v[186:189], v[118:121]
	s_waitcnt vmcnt(8)
	ds_write_b128 v131, v[2:5] offset:0
	ds_write_b128 v131, v[6:9] offset:8704
	ds_write_b128 v131, v[10:13] offset:17408
	ds_write_b128 v131, v[14:17] offset:26112
	ds_write_b64 v132, v[18:19] offset:34816
	s_cmp_eq_u32 s12, 0
	s_cbranch_scc1 .Lscan_nosc_3
	v_add_f32_e32 v142, v20, v124
	v_mul_f32_e32 v142, 0x3fb8aa3b, v142
	v_exp_f32_e32 v142, v142
	v_mov_b32_e32 v124, v21
	ds_write_b32 v133, v142 offset:0
.Lscan_nosc_3:
	s_add_u32 s3, s34, 3
	s_cmp_lt_u32 s3, 4
	s_cselect_b32 s4, s16, s17
	s_mul_i32 s5, s3, s15
	s_add_i32 s4, s4, s5
	s_lshl_b32 s4, s4, 16
	s_add_u32 s64, s28, s4
	s_addc_u32 s65, s29, 0
	s_cmp_eq_u32 s34, 0
	s_cselect_b32 s64, s30, s64
	s_cselect_b32 s65, s31, s65
	v_cvt_pk_bf16_f32 v206, v202, v203
	v_cvt_pk_bf16_f32 v207, v204, v205
	global_store_dwordx2 v130, v[206:207], s[64:65]
	s_waitcnt lgkmcnt(0)
	s_barrier
	s_add_u32 s34, s34, 4
	s_cmp_lt_u32 s34, 0x44
	s_cbranch_scc1 .Lscan_loop
	s_add_u32 s9, s9, s35
	s_cmp_lt_u32 s9, 0x100
	s_cbranch_scc1 .Lscan_item
.Lscan_done:
.LBB0_307:
	s_setprio 0
